# P7 ffnfix work rebalance: 768 consecutive items per workgroup (1.5 per thread), neighbouring rows on the same XCD
# speedup vs baseline: 1.0054x; 1.0054x over previous
.LBB0_1052:
	s_or_b64 exec, exec, s[0:1]
	v_readlane_b32 s98, v250, 0
	s_lshl_b32 s99, s94, 9
	s_lshl_b32 s100, s98, 9
	s_mov_b32 s101, 0x2ffff
	s_cmpk_lg_i32 s94, 0x100
	s_cbranch_scc1 .Lp7_nobal
	s_and_b32 s100, s98, 7
	s_lshl_b32 s100, s100, 5
	s_lshr_b32 s101, s98, 3
	s_or_b32 s100, s100, s101
	s_mul_i32 s100, s100, 0x300
	s_add_i32 s101, s100, 0x2ff
	s_movk_i32 s99, 0x200
.Lp7_nobal:
	v_add_u32_e32 v180, s100, v184
	v_mov_b32_e32 v181, 0
	v_lshlrev_b32_e32 v185, 3, v180
	v_mov_b32_e32 v142, s101
	v_mov_b32_e32 v143, 0
	v_mov_b32_e32 v144, s99
	s_mov_b64 s[0:1], 0x30000
	v_cmp_gt_u64_e32 vcc, s[0:1], v[180:181]
	s_waitcnt lgkmcnt(0)
	s_barrier
	s_and_saveexec_b64 s[0:1], vcc
	s_xor_b64 s[30:31], exec, s[0:1]
	s_cbranch_execz .LBB0_1090
	s_mov_b32 s46, -4
	s_mov_b64 s[44:45], 0
	s_mov_b32 s47, 3
	v_mov_b32_e32 v49, 0
	s_movk_i32 s2, 0x3000
	v_mov_b64_e32 v[50:51], s[56:57]
	v_mov_b64_e32 v[52:53], s[18:19]
	v_mov_b64_e32 v[54:55], v[180:181]
	s_branch .LBB0_1055
.LBB0_1054:
	s_or_b64 exec, exec, s[0:1]
	s_waitcnt vmcnt(6)
	v_pk_fma_f32 v[28:29], v[28:29], v[32:33], v[44:45]
	v_pk_fma_f32 v[30:31], v[30:31], v[34:35], v[46:47]
	v_pk_fma_f32 v[24:25], v[24:25], v[40:41], v[28:29]
	v_pk_fma_f32 v[26:27], v[26:27], v[42:43], v[30:31]
	v_pk_fma_f32 v[20:21], v[20:21], v[36:37], v[24:25]
	v_pk_fma_f32 v[22:23], v[22:23], v[38:39], v[26:27]
	v_mul_f32_e32 v24, 0x3d372713, v20
	v_mul_f32_e32 v24, v20, v24
	v_fma_f32 v24, v20, v24, v20
	v_mul_f32_e32 v24, 0x3fcc422a, v24
	v_mul_f32_e32 v24, 0xbfb8aa3b, v24
	v_exp_f32_e32 v24, v24
	v_add_u32_e32 v54, v144, v54
	s_mov_b64 s[0:1], 0x2ffff
	v_lshlrev_b32_e32 v48, 1, v48
	v_add_f32_e32 v24, 1.0, v24
	v_rcp_f32_e32 v24, v24
	v_cmp_lt_u64_e32 vcc, v[142:143], v[54:55]
	s_or_b64 s[44:45], vcc, s[44:45]
	v_mul_f32_e32 v20, v20, v24
	v_mul_f32_e32 v20, v16, v20
	v_mul_f32_e32 v16, 0x3d372713, v21
	v_mul_f32_e32 v16, v21, v16
	v_fma_f32 v16, v21, v16, v21
	v_mul_f32_e32 v16, 0x3fcc422a, v16
	v_mul_f32_e32 v16, 0xbfb8aa3b, v16
	v_exp_f32_e32 v16, v16
	s_nop 0
	v_add_f32_e32 v16, 1.0, v16
	v_rcp_f32_e32 v16, v16
	s_nop 0
	v_mul_f32_e32 v16, v21, v16
	v_mul_f32_e32 v21, v17, v16
	v_mul_f32_e32 v16, 0x3d372713, v22
	v_mul_f32_e32 v17, 0x3d372713, v23
	v_mul_f32_e32 v16, v22, v16
	v_mul_f32_e32 v17, v23, v17
	v_fma_f32 v16, v22, v16, v22
	v_fma_f32 v17, v23, v17, v23
	v_mul_f32_e32 v16, 0x3fcc422a, v16
	v_mul_f32_e32 v17, 0x3fcc422a, v17
	v_mul_f32_e32 v16, 0xbfb8aa3b, v16
	v_mul_f32_e32 v17, 0xbfb8aa3b, v17
	v_exp_f32_e32 v16, v16
	v_exp_f32_e32 v17, v17
	v_add_f32_e32 v16, 1.0, v16
	v_add_f32_e32 v17, 1.0, v17
	v_rcp_f32_e32 v16, v16
	v_rcp_f32_e32 v17, v17
	v_mul_f32_e32 v16, v22, v16
	v_mul_f32_e32 v17, v23, v17
	v_mul_f32_e32 v16, v18, v16
	v_mul_f32_e32 v17, v19, v17
	s_waitcnt vmcnt(0)
	v_pk_fma_f32 v[12:13], v[12:13], v[68:69], v[80:81]
	s_nop 0
	v_pk_fma_f32 v[8:9], v[8:9], v[72:73], v[12:13]
	v_pk_fma_f32 v[14:15], v[14:15], v[70:71], v[82:83]
	v_pk_fma_f32 v[4:5], v[4:5], v[76:77], v[8:9]
	v_pk_fma_f32 v[10:11], v[10:11], v[74:75], v[14:15]
	v_mul_f32_e32 v8, 0x3d372713, v4
	v_mul_f32_e32 v8, v4, v8
	v_fma_f32 v8, v4, v8, v4
	v_mul_f32_e32 v8, 0x3fcc422a, v8
	v_mul_f32_e32 v8, 0xbfb8aa3b, v8
	v_exp_f32_e32 v8, v8
	v_pk_fma_f32 v[6:7], v[6:7], v[78:79], v[10:11]
	v_add_f32_e32 v8, 1.0, v8
	v_rcp_f32_e32 v8, v8
	s_nop 0
	v_mul_f32_e32 v4, v4, v8
	v_mul_f32_e32 v0, v0, v4
	v_mul_f32_e32 v4, 0x3d372713, v5
	v_mul_f32_e32 v4, v5, v4
	v_fma_f32 v4, v5, v4, v5
	v_mul_f32_e32 v4, 0x3fcc422a, v4
	v_mul_f32_e32 v4, 0xbfb8aa3b, v4
	v_exp_f32_e32 v4, v4
	s_nop 0
	v_add_f32_e32 v4, 1.0, v4
	v_rcp_f32_e32 v4, v4
	s_nop 0
	v_mul_f32_e32 v4, v5, v4
	v_mul_f32_e32 v1, v1, v4
	v_mul_f32_e32 v4, 0x3d372713, v6
	v_mul_f32_e32 v4, v6, v4
	v_fma_f32 v4, v6, v4, v6
	v_mul_f32_e32 v4, 0x3fcc422a, v4
	v_mul_f32_e32 v4, 0xbfb8aa3b, v4
	v_exp_f32_e32 v4, v4
	s_nop 0
	v_add_f32_e32 v4, 1.0, v4
	v_rcp_f32_e32 v4, v4
	s_nop 0
	v_mul_f32_e32 v4, v6, v4
	v_mul_f32_e32 v2, v2, v4
	v_mul_f32_e32 v4, 0x3d372713, v7
	v_mul_f32_e32 v4, v7, v4
	v_fma_f32 v4, v7, v4, v7
	v_mul_f32_e32 v4, 0x3fcc422a, v4
	v_mul_f32_e32 v4, 0xbfb8aa3b, v4
	v_exp_f32_e32 v4, v4
	s_nop 0
	v_add_f32_e32 v4, 1.0, v4
	v_rcp_f32_e32 v4, v4
	s_nop 0
	v_mul_f32_e32 v4, v7, v4
	v_mul_f32_e32 v3, v3, v4
	v_cvt_pk_bf16_f32 v4, v20, v21
	v_cvt_pk_bf16_f32 v5, v16, v17
	v_cvt_pk_bf16_f32 v6, v0, v1
	v_mul_u32_u24_e32 v0, 0xc00, v66
	v_mov_b32_e32 v1, v49
	v_lshl_add_u64 v[0:1], v[0:1], 1, s[86:87]
	v_lshl_add_u64 v[0:1], v[0:1], 0, v[48:49]
	v_cvt_pk_bf16_f32 v7, v2, v3
	global_store_dwordx4 v[0:1], v[4:7], off
	s_andn2_b64 exec, exec, s[44:45]
	s_cbranch_execz .LBB0_1071

.LBB0_1071:
	s_or_b64 exec, exec, s[44:45]
	s_add_u32 s0, s92, 0x3e7d000
	s_addc_u32 s1, s93, 0
	s_add_u32 s26, s92, 0x3e7a000
	s_addc_u32 s27, s93, 0
	s_add_u32 s42, s90, 0x40ea000
	s_addc_u32 s43, s91, 0
	s_add_u32 s44, s90, 0x44f0000
	v_readlane_b32 s4, v250, 0
	s_movk_i32 s48, 0xff00
	s_addc_u32 s45, s91, 0
	v_readfirstlane_b32 s2, v144
	s_lshl_b32 s3, s2, 2
	s_lshl_b32 s2, s2, 3
	v_lshlrev_b32_e32 v56, 2, v180
	s_nop 0
	s_mov_b64 s[46:47], 0
	v_mov_b32_e32 v49, 0
	s_mov_b32 s49, 1
	s_movk_i32 s4, 0x3000
	v_readlane_b32 s5, v250, 1
	s_branch .LBB0_1073
.LBB0_1072:
	s_or_b64 exec, exec, s[34:35]
	v_pk_add_f32 v[4:5], v[4:5], v[8:9]
	v_pk_add_f32 v[6:7], v[6:7], v[10:11]
	v_pk_add_f32 v[4:5], v[4:5], v[12:13]
	v_pk_add_f32 v[6:7], v[6:7], v[14:15]
	v_pk_add_f32 v[4:5], v[4:5], v[16:17]
	v_pk_add_f32 v[6:7], v[6:7], v[18:19]
	s_nop 0
	v_pk_add_f32 v[20:21], v[4:5], v[20:21]
	v_pk_add_f32 v[22:23], v[6:7], v[22:23]
	v_mul_u32_u24_e32 v48, 0xc00, v57
	v_add_u32_e32 v180, v144, v180
	s_mov_b64 s[6:7], 0x2ffff
	v_cmp_lt_u64_e32 vcc, v[142:143], v[180:181]
	v_add_u32_e32 v185, s2, v185
	v_add_u32_e32 v56, s3, v56
	s_or_b64 s[46:47], vcc, s[46:47]
	s_nop 0
	v_pk_fma_f32 v[4:5], v[44:45], v[100:101], v[104:105]
	v_pk_fma_f32 v[6:7], v[46:47], v[102:103], v[106:107]
	s_nop 0
	v_pk_fma_f32 v[4:5], v[40:41], v[108:109], v[4:5]
	v_pk_fma_f32 v[6:7], v[42:43], v[110:111], v[6:7]
	s_nop 0
	v_pk_fma_f32 v[0:1], v[0:1], v[112:113], v[4:5]
	v_pk_fma_f32 v[2:3], v[2:3], v[114:115], v[6:7]
	v_mul_f32_e32 v4, 0x3d372713, v0
	v_mul_f32_e32 v4, v0, v4
	v_fma_f32 v4, v0, v4, v0
	v_mul_f32_e32 v4, 0x3fcc422a, v4
	v_mul_f32_e32 v4, 0xbfb8aa3b, v4
	v_exp_f32_e32 v4, v4
	s_nop 0
	v_add_f32_e32 v4, 1.0, v4
	v_rcp_f32_e32 v4, v4
	s_nop 0
	v_mul_f32_e32 v0, v0, v4
	v_mul_f32_e32 v4, 0x3d372713, v1
	v_mul_f32_e32 v4, v1, v4
	v_fma_f32 v4, v1, v4, v1
	v_mul_f32_e32 v4, 0x3fcc422a, v4
	v_mul_f32_e32 v4, 0xbfb8aa3b, v4
	v_exp_f32_e32 v4, v4
	v_mul_f32_e32 v0, v20, v0
	v_add_f32_e32 v4, 1.0, v4
	v_rcp_f32_e32 v4, v4
	s_nop 0
	v_mul_f32_e32 v1, v1, v4
	v_mul_f32_e32 v1, v21, v1
	v_cvt_pk_bf16_f32 v0, v0, v1
	v_mul_f32_e32 v1, 0x3d372713, v2
	v_mul_f32_e32 v1, v2, v1
	v_fma_f32 v1, v2, v1, v2
	v_mul_f32_e32 v1, 0x3fcc422a, v1
	v_mul_f32_e32 v1, 0xbfb8aa3b, v1
	v_exp_f32_e32 v1, v1
	s_nop 0
	v_add_f32_e32 v1, 1.0, v1
	v_rcp_f32_e32 v1, v1
	s_nop 0
	v_mul_f32_e32 v1, v2, v1
	v_mul_f32_e32 v2, 0x3d372713, v3
	v_mul_f32_e32 v2, v3, v2
	v_fma_f32 v2, v3, v2, v3
	v_mul_f32_e32 v2, 0x3fcc422a, v2
	v_mul_f32_e32 v2, 0xbfb8aa3b, v2
	v_exp_f32_e32 v2, v2
	v_mul_f32_e32 v1, v22, v1
	v_add_f32_e32 v2, 1.0, v2
	v_rcp_f32_e32 v2, v2
	s_nop 0
	v_mul_f32_e32 v2, v3, v2
	v_mul_f32_e32 v2, v23, v2
	v_cvt_pk_bf16_f32 v1, v1, v2
	v_lshl_add_u64 v[2:3], v[48:49], 1, s[86:87]
	v_lshl_add_u64 v[2:3], v[50:51], 1, v[2:3]
	global_store_dwordx2 v[2:3], v[0:1], off
	s_andn2_b64 exec, exec, s[46:47]
	s_cbranch_execz .LBB0_1089
